# Hyena hidden-row second layer: h1 broadcasts via v_readlane + scalar-operand fmac instead of one ds_bpermute and wait per term
# baseline (speedup 1.0000x reference)
; __device__ __forceinline__ void hy_hdn_row(const float* w1, const float* b1, const float* fq, const float* w2, const float* b2, float* hdn2, int t, int lane) {
;     ...
;     for (int i0 = 0; i0 < 64; i0 += 16) { float wv[16];
; #pragma unroll
;         for (int i = 0; i < 16; ++i) wv[i] = w2[(i0 + i) * 64 + lane];
; #pragma unroll
;         for (int i = 0; i < 16; ++i) pre2 += __shfl(h1, i0 + i) * wv[i]; }
;     hdn2[t * 64 + lane] = sinf(f * pre2);
.LBB0_277:
	global_load_dword v51, v[44:45], off
	global_load_dword v55, v[44:45], off offset:256
	global_load_dword v64, v[44:45], off offset:512
	global_load_dword v52, v[44:45], off offset:768
	global_load_dword v53, v[44:45], off offset:1024
	global_load_dword v56, v[44:45], off offset:1280
	global_load_dword v57, v[44:45], off offset:1536
	global_load_dword v58, v[44:45], off offset:1792
	global_load_dword v59, v[44:45], off offset:2048
	global_load_dword v60, v[44:45], off offset:2304
	global_load_dword v61, v[44:45], off offset:2560
	global_load_dword v62, v[44:45], off offset:2816
	global_load_dword v63, v[44:45], off offset:3072
	global_load_dword v66, v[44:45], off offset:3328
	global_load_dword v67, v[44:45], off offset:3584
	global_load_dword v70, v[44:45], off offset:3840
	s_add_i32 s4, s4, 16
	v_lshl_add_u64 v[44:45], v[44:45], 0, s[6:7]
	s_mov_b32 s84, s4
	v_readlane_b32 s68, v48, s84
	s_add_i32 s84, s84, 1
	v_readlane_b32 s69, v48, s84
	s_add_i32 s84, s84, 1
	v_readlane_b32 s70, v48, s84
	s_add_i32 s84, s84, 1
	v_readlane_b32 s71, v48, s84
	s_add_i32 s84, s84, 1
	v_readlane_b32 s72, v48, s84
	s_add_i32 s84, s84, 1
	v_readlane_b32 s73, v48, s84
	s_add_i32 s84, s84, 1
	v_readlane_b32 s74, v48, s84
	s_add_i32 s84, s84, 1
	v_readlane_b32 s75, v48, s84
	s_add_i32 s84, s84, 1
	v_readlane_b32 s76, v48, s84
	s_add_i32 s84, s84, 1
	v_readlane_b32 s77, v48, s84
	s_add_i32 s84, s84, 1
	v_readlane_b32 s78, v48, s84
	s_add_i32 s84, s84, 1
	v_readlane_b32 s79, v48, s84
	s_add_i32 s84, s84, 1
	v_readlane_b32 s80, v48, s84
	s_add_i32 s84, s84, 1
	v_readlane_b32 s81, v48, s84
	s_add_i32 s84, s84, 1
	v_readlane_b32 s82, v48, s84
	s_add_i32 s84, s84, 1
	v_readlane_b32 s83, v48, s84
	s_cmp_lt_u32 s4, 48
	s_waitcnt vmcnt(15)
	v_fmac_f32_e32 v50, s68, v51
	s_waitcnt vmcnt(14)
	v_fmac_f32_e32 v50, s69, v55
	s_waitcnt vmcnt(13)
	v_fmac_f32_e32 v50, s70, v64
	s_waitcnt vmcnt(12)
	v_fmac_f32_e32 v50, s71, v52
	s_waitcnt vmcnt(11)
	v_fmac_f32_e32 v50, s72, v53
	s_waitcnt vmcnt(10)
	v_fmac_f32_e32 v50, s73, v56
	s_waitcnt vmcnt(9)
	v_fmac_f32_e32 v50, s74, v57
	s_waitcnt vmcnt(8)
	v_fmac_f32_e32 v50, s75, v58
	s_waitcnt vmcnt(7)
	v_fmac_f32_e32 v50, s76, v59
	s_waitcnt vmcnt(6)
	v_fmac_f32_e32 v50, s77, v60
	s_waitcnt vmcnt(5)
	v_fmac_f32_e32 v50, s78, v61
	s_waitcnt vmcnt(4)
	v_fmac_f32_e32 v50, s79, v62
	s_waitcnt vmcnt(3)
	v_fmac_f32_e32 v50, s80, v63
	s_waitcnt vmcnt(2)
	v_fmac_f32_e32 v50, s81, v66
	s_waitcnt vmcnt(1)
	v_fmac_f32_e32 v50, s82, v67
	s_waitcnt vmcnt(0)
	v_fmac_f32_e32 v50, s83, v70
	s_cbranch_scc1 .LBB0_277
	v_mul_f32_e32 v44, v54, v50
	v_and_b32_e32 v45, 0x7fffffff, v44
	v_cmp_nlt_f32_e64 s[4:5], |v44|, s19
	s_and_saveexec_b64 s[6:7], s[4:5]
	s_xor_b64 s[10:11], exec, s[6:7]
	s_cbranch_execz .LBB0_280
	v_lshrrev_b32_e32 v48, 23, v45
	v_add_u32_e32 v48, 0xffffff88, v48
	v_cmp_lt_u32_e32 vcc, 63, v48
	v_not_b32_e32 v49, 63
	v_not_b32_e32 v50, 31
	v_cndmask_b32_e32 v49, 0, v49, vcc
	v_add_u32_e32 v48, v49, v48
	v_cmp_lt_u32_e64 s[4:5], 31, v48
	s_mov_b32 s8, 0xfe5163ab
	s_nop 0
	v_cndmask_b32_e64 v49, 0, v50, s[4:5]
	v_add_u32_e32 v48, v49, v48
	v_cmp_lt_u32_e64 s[6:7], 31, v48
	s_nop 1
	v_cndmask_b32_e64 v49, 0, v50, s[6:7]
	v_add_u32_e32 v62, v49, v48
	v_and_b32_e32 v48, 0x7fffff, v45
	v_or_b32_e32 v60, 0x800000, v48
	v_mad_u64_u32 v[48:49], s[8:9], v60, s8, 0
	v_mov_b32_e32 v64, v49
	s_mov_b32 s8, 0x3c439041
	v_mad_u64_u32 v[50:51], s[8:9], v60, s8, v[64:65]
	v_mov_b32_e32 v64, v51
	s_mov_b32 s8, 0xdb629599
	v_mad_u64_u32 v[52:53], s[8:9], v60, s8, v[64:65]
	v_mov_b32_e32 v64, v53
	s_mov_b32 s8, 0xf534ddc0
	v_mad_u64_u32 v[54:55], s[8:9], v60, s8, v[64:65]
	v_mov_b32_e32 v64, v55
	s_mov_b32 s8, 0xfc2757d1
	v_mad_u64_u32 v[56:57], s[8:9], v60, s8, v[64:65]
	v_mov_b32_e32 v64, v57
	s_mov_b32 s8, 0x4e441529
	v_mad_u64_u32 v[58:59], s[8:9], v60, s8, v[64:65]
	v_mov_b32_e32 v64, v59
	s_mov_b32 s8, 0xa2f9836e
	v_mad_u64_u32 v[60:61], s[8:9], v60, s8, v[64:65]
	v_cndmask_b32_e32 v49, v58, v54, vcc
	v_cndmask_b32_e32 v51, v60, v56, vcc
	v_cndmask_b32_e32 v55, v61, v58, vcc
	v_cndmask_b32_e64 v53, v51, v49, s[4:5]
	v_cndmask_b32_e64 v51, v55, v51, s[4:5]
	v_cndmask_b32_e32 v55, v56, v52, vcc
	v_cndmask_b32_e64 v49, v49, v55, s[4:5]
	v_cndmask_b32_e32 v50, v54, v50, vcc
	v_cndmask_b32_e64 v51, v51, v53, s[6:7]
	v_cndmask_b32_e64 v53, v53, v49, s[6:7]
	v_sub_u32_e32 v56, 32, v62
	v_cndmask_b32_e64 v54, v55, v50, s[4:5]
	v_alignbit_b32 v57, v51, v53, v56
	v_cmp_eq_u32_e64 s[8:9], 0, v62
	v_cndmask_b32_e64 v49, v49, v54, s[6:7]
	v_alignbit_b32 v55, v53, v49, v56
	v_cndmask_b32_e64 v51, v57, v51, s[8:9]
	v_cndmask_b32_e32 v48, v52, v48, vcc
	v_cndmask_b32_e64 v53, v55, v53, s[8:9]
	v_bfe_u32 v58, v51, 29, 1
	v_cndmask_b32_e64 v48, v50, v48, s[4:5]
	v_alignbit_b32 v55, v51, v53, 30
	v_sub_u32_e32 v59, 0, v58
	v_cndmask_b32_e64 v48, v54, v48, s[6:7]
	v_xor_b32_e32 v55, v55, v59
	v_alignbit_b32 v50, v49, v48, v56
	v_cndmask_b32_e64 v49, v50, v49, s[8:9]
	v_ffbh_u32_e32 v52, v55
	v_alignbit_b32 v50, v53, v49, 30
	v_min_u32_e32 v52, 32, v52
	v_alignbit_b32 v48, v49, v48, 30
	v_xor_b32_e32 v50, v50, v59
	v_sub_u32_e32 v53, 31, v52
	v_xor_b32_e32 v48, v48, v59
	v_alignbit_b32 v54, v55, v50, v53
	v_alignbit_b32 v48, v50, v48, v53
	v_alignbit_b32 v49, v54, v48, 9
	v_ffbh_u32_e32 v50, v49
	v_min_u32_e32 v50, 32, v50
	v_lshrrev_b32_e32 v57, 29, v51
	v_not_b32_e32 v53, v50
	v_alignbit_b32 v48, v49, v48, v53
	v_lshlrev_b32_e32 v49, 31, v57
	v_or_b32_e32 v53, 0x33000000, v49
	v_add_lshl_u32 v50, v50, v52, 23
	v_lshrrev_b32_e32 v48, 9, v48
	v_sub_u32_e32 v50, v53, v50
	v_or_b32_e32 v49, 0.5, v49
	v_lshlrev_b32_e32 v52, 23, v52
	v_or_b32_e32 v48, v50, v48
	v_lshrrev_b32_e32 v50, 9, v54
	v_sub_u32_e32 v49, v49, v52
	v_or_b32_e32 v49, v50, v49
	v_mul_f32_e32 v50, 0x3fc90fda, v49
	v_fma_f32 v52, v49, s20, -v50
	v_fmac_f32_e32 v52, 0x33a22168, v49
	v_fmac_f32_e32 v52, 0x3fc90fda, v48
	v_lshrrev_b32_e32 v48, 30, v51
	v_add_f32_e32 v49, v50, v52
	v_add_u32_e32 v48, v58, v48
